# fa (prompt instance) epilogue stores also widened to dwordx4 via v_permlane16_swap using four free quads; placement preserved
# speedup vs baseline: 1.0069x; 1.0034x over previous
.LBB0_59:
	s_ashr_i32 s31, s30, 31
	s_lshl_b64 s[14:15], s[30:31], 17
	v_readlane_b32 s18, v254, 29
	v_mov_b64_e32 v[0:1], 0x200
	v_readlane_b32 s19, v254, 30
	s_add_u32 s34, s18, s14
	v_cmp_lt_i64_e32 vcc, s[8:9], v[0:1]
	s_addc_u32 s35, s19, s15
	s_and_b64 s[14:15], vcc, exec
	s_cselect_b32 s45, s35, s41
	s_cselect_b32 s44, s34, s40
	s_ashr_i32 s13, s12, 31
	s_lshl_b64 s[14:15], s[12:13], 17
	s_add_u32 s18, s94, s14
	s_addc_u32 s19, s95, s15
	s_and_b64 s[14:15], vcc, exec
	s_cselect_b32 s15, s19, s43
	s_cselect_b32 s14, s18, s42
	s_add_i32 s47, 16, 0x10000
	v_add_u32_e32 v115, s47, v109
	ds_read_b128 v[0:3], v115
	ds_read_b128 v[4:7], v115 offset:1024
	ds_read_b128 v[8:11], v115 offset:2048
	ds_read_b128 v[12:15], v115 offset:3072
	v_mov_b64_e32 v[112:113], 0x2ff
	v_mov_b32_e32 v111, 0x3e642e9d
	v_mov_b32_e32 v243, 0xbf1f24be
	s_add_u32 s48, s40, 0x10080
	s_addc_u32 s49, s41, 0
	s_add_i32 s92, s16, 0xc000
	v_lshl_add_u64 v[48:49], s[48:49], 0, v[106:107]
	s_mov_b32 m0, s92
	s_add_i32 s1, s16, 0xe000
	ds_read_b128 v[16:19], v114
	ds_read_b128 v[20:23], v114 offset:1024
	ds_read_b128 v[24:27], v114 offset:2048
	ds_read_b128 v[28:31], v114 offset:3072
	ds_read_b128 v[32:35], v114 offset:4096
	ds_read_b128 v[36:39], v114 offset:5120
	ds_read_b128 v[40:43], v114 offset:6144
	ds_read_b128 v[44:47], v114 offset:7168
	global_load_lds_dwordx4 v[48:49], off
	v_lshl_add_u64 v[48:49], s[48:49], 0, v[104:105]
	s_mov_b32 m0, s1
	s_nop 0
	global_load_lds_dwordx4 v[48:49], off
	s_waitcnt lgkmcnt(8)
	s_barrier
	s_waitcnt lgkmcnt(0)
	s_setprio 1
	s_waitcnt lgkmcnt(0)
	v_mfma_f32_16x16x32_bf16 v[48:51], v[0:3], v[16:19], 0
	v_mfma_f32_16x16x32_bf16 v[52:55], v[8:11], v[16:19], 0
	v_mfma_f32_16x16x32_bf16 v[56:59], v[0:3], v[24:27], 0
	v_mfma_f32_16x16x32_bf16 v[60:63], v[8:11], v[24:27], 0
	v_mfma_f32_16x16x32_bf16 v[64:67], v[0:3], v[32:35], 0
	v_mfma_f32_16x16x32_bf16 v[68:71], v[8:11], v[32:35], 0
	v_mfma_f32_16x16x32_bf16 v[72:75], v[0:3], v[40:43], 0
	v_mfma_f32_16x16x32_bf16 v[76:79], v[8:11], v[40:43], 0
	v_mfma_f32_16x16x32_bf16 v[48:51], v[4:7], v[20:23], v[48:51]
	v_mfma_f32_16x16x32_bf16 v[52:55], v[12:15], v[20:23], v[52:55]
	v_mfma_f32_16x16x32_bf16 v[56:59], v[4:7], v[28:31], v[56:59]
	v_mfma_f32_16x16x32_bf16 v[60:63], v[12:15], v[28:31], v[60:63]
	v_mfma_f32_16x16x32_bf16 v[64:67], v[4:7], v[36:39], v[64:67]
	v_mfma_f32_16x16x32_bf16 v[68:71], v[12:15], v[36:39], v[68:71]
	v_mfma_f32_16x16x32_bf16 v[72:75], v[4:7], v[44:47], v[72:75]
	v_mfma_f32_16x16x32_bf16 v[76:79], v[12:15], v[44:47], v[76:79]
	s_setprio 0
	s_barrier
	s_add_i32 vcc_lo, 16, 0x14000
	v_lshl_add_u64 v[130:131], s[42:43], 0, v[106:107]
	s_mov_b64 s[48:49], 0x100
	s_add_i32 s47, s47, s5
	v_add_u32_e32 v128, vcc_lo, v109
	v_lshl_add_u64 v[96:97], v[130:131], 0, s[48:49]
	s_mov_b32 m0, s47
	v_lshl_add_u64 v[132:133], s[42:43], 0, v[104:105]
	s_add_i32 s13, s47, 0x2000
	ds_read_b128 v[80:83], v128
	ds_read_b128 v[84:87], v128 offset:1024
	ds_read_b128 v[88:91], v128 offset:2048
	ds_read_b128 v[92:95], v128 offset:3072
	global_load_lds_dwordx4 v[96:97], off
	v_lshl_add_u64 v[96:97], v[132:133], 0, s[48:49]
	s_mov_b32 m0, s13
	s_nop 0
	global_load_lds_dwordx4 v[96:97], off
	s_barrier
	s_waitcnt lgkmcnt(0)
	s_setprio 1
	s_waitcnt lgkmcnt(0)
	v_mfma_f32_16x16x32_bf16 v[96:99], v[80:83], v[16:19], 0
	v_mfma_f32_16x16x32_bf16 v[16:19], v[88:91], v[16:19], 0
	v_mfma_f32_16x16x32_bf16 v[96:99], v[84:87], v[20:23], v[96:99]
	v_mfma_f32_16x16x32_bf16 v[16:19], v[92:95], v[20:23], v[16:19]
	v_mfma_f32_16x16x32_bf16 v[20:23], v[80:83], v[24:27], 0
	v_mfma_f32_16x16x32_bf16 v[24:27], v[88:91], v[24:27], 0
	v_mfma_f32_16x16x32_bf16 v[20:23], v[84:87], v[28:31], v[20:23]
	v_mfma_f32_16x16x32_bf16 v[24:27], v[92:95], v[28:31], v[24:27]
	v_mfma_f32_16x16x32_bf16 v[28:31], v[80:83], v[32:35], 0
	v_mfma_f32_16x16x32_bf16 v[32:35], v[88:91], v[32:35], 0
	v_mfma_f32_16x16x32_bf16 v[28:31], v[84:87], v[36:39], v[28:31]
	v_mfma_f32_16x16x32_bf16 v[32:35], v[92:95], v[36:39], v[32:35]
	v_mfma_f32_16x16x32_bf16 v[36:39], v[80:83], v[40:43], 0
	v_mfma_f32_16x16x32_bf16 v[40:43], v[88:91], v[40:43], 0
	v_mfma_f32_16x16x32_bf16 v[36:39], v[84:87], v[44:47], v[36:39]
	v_mfma_f32_16x16x32_bf16 v[40:43], v[92:95], v[44:47], v[40:43]
	s_setprio 0
	v_lshl_add_u64 v[134:135], s[40:41], 0, v[106:107]
	s_mov_b32 m0, s16
	v_lshl_add_u64 v[136:137], v[134:135], 0, s[48:49]
	s_barrier
	ds_read_b128 v[44:47], v114 offset:16384
	ds_read_b128 v[100:103], v114 offset:17408
	ds_read_b128 v[116:119], v114 offset:18432
	ds_read_b128 v[120:123], v114 offset:19456
	ds_read_b128 v[124:127], v114 offset:20480
	ds_read_b128 v[144:147], v114 offset:21504
	ds_read_b128 v[148:151], v114 offset:22528
	ds_read_b128 v[152:155], v114 offset:23552
	global_load_lds_dwordx4 v[136:137], off
	v_lshl_add_u64 v[136:137], s[40:41], 0, v[104:105]
	v_lshl_add_u64 v[156:157], v[136:137], 0, s[48:49]
	s_mov_b32 m0, s17
	s_nop 0
	global_load_lds_dwordx4 v[156:157], off
	s_barrier
	s_waitcnt lgkmcnt(0)
	s_setprio 1
	s_waitcnt lgkmcnt(0)
	v_mfma_f32_16x16x32_bf16 v[156:159], v[0:3], v[44:47], 0
	v_mfma_f32_16x16x32_bf16 v[164:167], v[0:3], v[116:119], 0
	v_mfma_f32_16x16x32_bf16 v[172:175], v[0:3], v[124:127], 0
	v_mfma_f32_16x16x32_bf16 v[0:3], v[0:3], v[148:151], 0
	v_mfma_f32_16x16x32_bf16 v[156:159], v[4:7], v[100:103], v[156:159]
	v_mfma_f32_16x16x32_bf16 v[160:163], v[8:11], v[44:47], 0
	v_mfma_f32_16x16x32_bf16 v[164:167], v[4:7], v[120:123], v[164:167]
	v_mfma_f32_16x16x32_bf16 v[168:171], v[8:11], v[116:119], 0
	v_mfma_f32_16x16x32_bf16 v[172:175], v[4:7], v[144:147], v[172:175]
	v_mfma_f32_16x16x32_bf16 v[176:179], v[8:11], v[124:127], 0
	v_mfma_f32_16x16x32_bf16 v[0:3], v[4:7], v[152:155], v[0:3]
	v_mfma_f32_16x16x32_bf16 v[4:7], v[8:11], v[148:151], 0
	v_mfma_f32_16x16x32_bf16 v[160:163], v[12:15], v[100:103], v[160:163]
	v_mfma_f32_16x16x32_bf16 v[168:171], v[12:15], v[120:123], v[168:171]
	v_mfma_f32_16x16x32_bf16 v[176:179], v[12:15], v[144:147], v[176:179]
	v_mfma_f32_16x16x32_bf16 v[4:7], v[12:15], v[152:155], v[4:7]
	s_setprio 0
	s_barrier
	s_add_u32 s48, s42, 0x10100
	s_addc_u32 s49, s43, 0
	s_add_i32 vcc_lo, vcc_lo, s5
	v_lshl_add_u64 v[8:9], s[48:49], 0, v[106:107]
	s_mov_b32 m0, vcc_lo
	s_add_i32 s31, vcc_lo, 0x2000
	global_load_lds_dwordx4 v[8:9], off
	v_lshl_add_u64 v[8:9], s[48:49], 0, v[104:105]
	s_mov_b32 m0, s31
	s_nop 0
	global_load_lds_dwordx4 v[8:9], off
	s_waitcnt vmcnt(6)
	s_barrier
	s_setprio 1
	v_mfma_f32_16x16x32_bf16 v[8:11], v[80:83], v[44:47], 0
	v_mfma_f32_16x16x32_bf16 v[12:15], v[88:91], v[44:47], 0
	v_mfma_f32_16x16x32_bf16 v[8:11], v[84:87], v[100:103], v[8:11]
	v_mfma_f32_16x16x32_bf16 v[12:15], v[92:95], v[100:103], v[12:15]
	v_mfma_f32_16x16x32_bf16 v[44:47], v[80:83], v[116:119], 0
	v_mfma_f32_16x16x32_bf16 v[100:103], v[88:91], v[116:119], 0
	v_mfma_f32_16x16x32_bf16 v[116:119], v[80:83], v[124:127], 0
	v_mfma_f32_16x16x32_bf16 v[80:83], v[80:83], v[148:151], 0
	v_mfma_f32_16x16x32_bf16 v[44:47], v[84:87], v[120:123], v[44:47]
	v_mfma_f32_16x16x32_bf16 v[100:103], v[92:95], v[120:123], v[100:103]
	v_mfma_f32_16x16x32_bf16 v[116:119], v[84:87], v[144:147], v[116:119]
	v_mfma_f32_16x16x32_bf16 v[120:123], v[88:91], v[124:127], 0
	v_mfma_f32_16x16x32_bf16 v[80:83], v[84:87], v[152:155], v[80:83]
	v_mfma_f32_16x16x32_bf16 v[84:87], v[88:91], v[148:151], 0
	v_mfma_f32_16x16x32_bf16 v[120:123], v[92:95], v[144:147], v[120:123]
	v_mfma_f32_16x16x32_bf16 v[84:87], v[92:95], v[152:155], v[84:87]
	s_setprio 0
	s_add_i32 s20, 16, 0x18000
	v_add_u32_e32 v143, s20, v109
	s_barrier
	ds_read_b128 v[88:91], v143
	ds_read_b128 v[92:95], v143 offset:1024
	ds_read_b128 v[124:127], v143 offset:2048
	ds_read_b128 v[144:147], v143 offset:3072
	s_add_u32 s48, s40, 0x10100
	s_addc_u32 s49, s41, 0
	s_mov_b32 m0, s36
	v_lshl_add_u64 v[204:205], s[48:49], 0, v[106:107]
	ds_read_b128 v[148:151], v114 offset:32768
	ds_read_b128 v[152:155], v114 offset:33792
	ds_read_b128 v[180:183], v114 offset:34816
	ds_read_b128 v[184:187], v114 offset:35840
	ds_read_b128 v[188:191], v114 offset:36864
	ds_read_b128 v[192:195], v114 offset:37888
	ds_read_b128 v[196:199], v114 offset:38912
	ds_read_b128 v[200:203], v114 offset:39936
	global_load_lds_dwordx4 v[204:205], off
	v_lshl_add_u64 v[204:205], s[48:49], 0, v[104:105]
	s_mov_b32 m0, s37
	s_nop 0
	global_load_lds_dwordx4 v[204:205], off
	s_waitcnt lgkmcnt(8)
	s_barrier
	s_waitcnt lgkmcnt(0)
	s_setprio 1
	s_waitcnt lgkmcnt(0)
	v_mfma_f32_16x16x32_bf16 v[48:51], v[88:91], v[148:151], v[48:51]
	v_mfma_f32_16x16x32_bf16 v[52:55], v[124:127], v[148:151], v[52:55]
	v_mfma_f32_16x16x32_bf16 v[56:59], v[88:91], v[180:183], v[56:59]
	v_mfma_f32_16x16x32_bf16 v[60:63], v[124:127], v[180:183], v[60:63]
	v_mfma_f32_16x16x32_bf16 v[64:67], v[88:91], v[188:191], v[64:67]
	v_mfma_f32_16x16x32_bf16 v[68:71], v[124:127], v[188:191], v[68:71]
	v_mfma_f32_16x16x32_bf16 v[72:75], v[88:91], v[196:199], v[72:75]
	v_mfma_f32_16x16x32_bf16 v[76:79], v[124:127], v[196:199], v[76:79]
	v_mfma_f32_16x16x32_bf16 v[48:51], v[92:95], v[152:155], v[48:51]
	v_mfma_f32_16x16x32_bf16 v[52:55], v[144:147], v[152:155], v[52:55]
	v_mfma_f32_16x16x32_bf16 v[56:59], v[92:95], v[184:187], v[56:59]
	v_mfma_f32_16x16x32_bf16 v[60:63], v[144:147], v[184:187], v[60:63]
	v_mfma_f32_16x16x32_bf16 v[64:67], v[92:95], v[192:195], v[64:67]
	v_mfma_f32_16x16x32_bf16 v[68:71], v[144:147], v[192:195], v[68:71]
	v_mfma_f32_16x16x32_bf16 v[72:75], v[92:95], v[200:203], v[72:75]
	v_mfma_f32_16x16x32_bf16 v[76:79], v[144:147], v[200:203], v[76:79]
	s_setprio 0
	s_barrier
	s_add_i32 s49, 16, 0x1c000
	s_mov_b64 s[50:51], 0x180
	s_add_i32 s48, s20, s5
	v_add_u32_e32 v242, s49, v109
	v_lshl_add_u64 v[130:131], v[130:131], 0, s[50:51]
	s_mov_b32 m0, s48
	s_add_i32 vcc_hi, s48, 0x2000
	ds_read_b128 v[204:207], v242
	ds_read_b128 v[208:211], v242 offset:1024
	ds_read_b128 v[212:215], v242 offset:2048
	ds_read_b128 v[216:219], v242 offset:3072
	global_load_lds_dwordx4 v[130:131], off
	v_lshl_add_u64 v[130:131], v[132:133], 0, s[50:51]
	s_mov_b32 m0, vcc_hi
	s_nop 0
	global_load_lds_dwordx4 v[130:131], off
	s_barrier
	s_waitcnt lgkmcnt(0)
	s_setprio 1
	s_waitcnt lgkmcnt(0)
	v_mfma_f32_16x16x32_bf16 v[96:99], v[204:207], v[148:151], v[96:99]
	v_mfma_f32_16x16x32_bf16 v[16:19], v[212:215], v[148:151], v[16:19]
	v_mfma_f32_16x16x32_bf16 v[20:23], v[204:207], v[180:183], v[20:23]
	v_mfma_f32_16x16x32_bf16 v[24:27], v[212:215], v[180:183], v[24:27]
	v_mfma_f32_16x16x32_bf16 v[28:31], v[204:207], v[188:191], v[28:31]
	v_mfma_f32_16x16x32_bf16 v[32:35], v[212:215], v[188:191], v[32:35]
	v_mfma_f32_16x16x32_bf16 v[36:39], v[204:207], v[196:199], v[36:39]
	v_mfma_f32_16x16x32_bf16 v[40:43], v[212:215], v[196:199], v[40:43]
	v_mfma_f32_16x16x32_bf16 v[96:99], v[208:211], v[152:155], v[96:99]
	v_mfma_f32_16x16x32_bf16 v[16:19], v[216:219], v[152:155], v[16:19]
	v_mfma_f32_16x16x32_bf16 v[20:23], v[208:211], v[184:187], v[20:23]
	v_mfma_f32_16x16x32_bf16 v[24:27], v[216:219], v[184:187], v[24:27]
	v_mfma_f32_16x16x32_bf16 v[28:31], v[208:211], v[192:195], v[28:31]
	v_mfma_f32_16x16x32_bf16 v[32:35], v[216:219], v[192:195], v[32:35]
	v_mfma_f32_16x16x32_bf16 v[36:39], v[208:211], v[200:203], v[36:39]
	v_mfma_f32_16x16x32_bf16 v[40:43], v[216:219], v[200:203], v[40:43]
	s_setprio 0
	s_mov_b32 m0, s24
	v_lshl_add_u64 v[130:131], v[134:135], 0, s[50:51]
	s_barrier
	ds_read_b128 v[148:151], v114 offset:49152
	ds_read_b128 v[152:155], v114 offset:50176
	ds_read_b128 v[180:183], v114 offset:51200
	ds_read_b128 v[184:187], v114 offset:52224
	ds_read_b128 v[188:191], v114 offset:53248
	ds_read_b128 v[192:195], v114 offset:54272
	ds_read_b128 v[196:199], v114 offset:55296
	ds_read_b128 v[200:203], v114 offset:56320
	global_load_lds_dwordx4 v[130:131], off
	v_lshl_add_u64 v[130:131], v[136:137], 0, s[50:51]
	s_mov_b32 m0, s25
	s_nop 0
	global_load_lds_dwordx4 v[130:131], off
	s_barrier
	s_waitcnt lgkmcnt(0)
	s_setprio 1
	s_waitcnt lgkmcnt(0)
	v_mfma_f32_16x16x32_bf16 v[156:159], v[88:91], v[148:151], v[156:159]
	v_mfma_f32_16x16x32_bf16 v[160:163], v[124:127], v[148:151], v[160:163]
	v_mfma_f32_16x16x32_bf16 v[164:167], v[88:91], v[180:183], v[164:167]
	v_mfma_f32_16x16x32_bf16 v[168:171], v[124:127], v[180:183], v[168:171]
	v_mfma_f32_16x16x32_bf16 v[172:175], v[88:91], v[188:191], v[172:175]
	v_mfma_f32_16x16x32_bf16 v[176:179], v[124:127], v[188:191], v[176:179]
	v_mfma_f32_16x16x32_bf16 v[0:3], v[88:91], v[196:199], v[0:3]
	v_mfma_f32_16x16x32_bf16 v[4:7], v[124:127], v[196:199], v[4:7]
	v_mfma_f32_16x16x32_bf16 v[156:159], v[92:95], v[152:155], v[156:159]
	v_mfma_f32_16x16x32_bf16 v[160:163], v[144:147], v[152:155], v[160:163]
	v_mfma_f32_16x16x32_bf16 v[164:167], v[92:95], v[184:187], v[164:167]
	v_mfma_f32_16x16x32_bf16 v[168:171], v[144:147], v[184:187], v[168:171]
	v_mfma_f32_16x16x32_bf16 v[172:175], v[92:95], v[192:195], v[172:175]
	v_mfma_f32_16x16x32_bf16 v[176:179], v[144:147], v[192:195], v[176:179]
	v_mfma_f32_16x16x32_bf16 v[0:3], v[92:95], v[200:203], v[0:3]
	v_mfma_f32_16x16x32_bf16 v[4:7], v[144:147], v[200:203], v[4:7]
	s_setprio 0
	s_barrier
	s_add_u32 s50, s42, 0x10180
	s_addc_u32 s51, s43, 0
	s_add_i32 s42, s49, s5
	v_lshl_add_u64 v[88:89], s[50:51], 0, v[106:107]
	s_mov_b32 m0, s42
	s_add_i32 s20, s42, 0x2000
	global_load_lds_dwordx4 v[88:89], off
	v_lshl_add_u64 v[88:89], s[50:51], 0, v[104:105]
	s_mov_b32 m0, s20
	s_nop 0
	global_load_lds_dwordx4 v[88:89], off
	s_waitcnt vmcnt(6)
	s_barrier
	s_setprio 1
	v_mfma_f32_16x16x32_bf16 v[8:11], v[204:207], v[148:151], v[8:11]
	v_mfma_f32_16x16x32_bf16 v[12:15], v[212:215], v[148:151], v[12:15]
	v_mfma_f32_16x16x32_bf16 v[44:47], v[204:207], v[180:183], v[44:47]
	v_mfma_f32_16x16x32_bf16 v[88:91], v[212:215], v[180:183], v[100:103]
	v_mfma_f32_16x16x32_bf16 v[92:95], v[204:207], v[188:191], v[116:119]
	v_mfma_f32_16x16x32_bf16 v[100:103], v[212:215], v[188:191], v[120:123]
	v_mfma_f32_16x16x32_bf16 v[80:83], v[204:207], v[196:199], v[80:83]
	v_mfma_f32_16x16x32_bf16 v[84:87], v[212:215], v[196:199], v[84:87]
	v_mfma_f32_16x16x32_bf16 v[8:11], v[208:211], v[152:155], v[8:11]
	v_mfma_f32_16x16x32_bf16 v[12:15], v[216:219], v[152:155], v[12:15]
	v_mfma_f32_16x16x32_bf16 v[44:47], v[208:211], v[184:187], v[44:47]
	v_mfma_f32_16x16x32_bf16 v[88:91], v[216:219], v[184:187], v[88:91]
	v_mfma_f32_16x16x32_bf16 v[92:95], v[208:211], v[192:195], v[92:95]
	v_mfma_f32_16x16x32_bf16 v[100:103], v[216:219], v[192:195], v[100:103]
	v_mfma_f32_16x16x32_bf16 v[80:83], v[208:211], v[200:203], v[80:83]
	v_mfma_f32_16x16x32_bf16 v[84:87], v[216:219], v[200:203], v[84:87]
	s_setprio 0
	s_barrier
	ds_read_b128 v[116:119], v115
	ds_read_b128 v[120:123], v115 offset:1024
	ds_read_b128 v[124:127], v115 offset:2048
	ds_read_b128 v[144:147], v115 offset:3072
	s_add_u32 s40, s40, 0x10180
	s_addc_u32 s41, s41, 0
	s_mov_b32 m0, s92
	v_lshl_add_u64 v[130:131], s[40:41], 0, v[106:107]
	ds_read_b128 v[148:151], v114
	ds_read_b128 v[152:155], v114 offset:1024
	ds_read_b128 v[180:183], v114 offset:2048
	ds_read_b128 v[184:187], v114 offset:3072
	ds_read_b128 v[188:191], v114 offset:4096
	ds_read_b128 v[192:195], v114 offset:5120
	ds_read_b128 v[196:199], v114 offset:6144
	ds_read_b128 v[200:203], v114 offset:7168
	global_load_lds_dwordx4 v[130:131], off
	v_lshl_add_u64 v[130:131], s[40:41], 0, v[104:105]
	s_mov_b32 m0, s1
	s_nop 0
	global_load_lds_dwordx4 v[130:131], off
	s_waitcnt lgkmcnt(8)
	s_barrier
	s_waitcnt lgkmcnt(0)
	s_setprio 1
	s_waitcnt lgkmcnt(0)
	v_mfma_f32_16x16x32_bf16 v[64:67], v[116:119], v[188:191], v[64:67]
	v_mfma_f32_16x16x32_bf16 v[204:207], v[120:123], v[192:195], v[64:67]
	v_mfma_f32_16x16x32_bf16 v[64:67], v[124:127], v[188:191], v[68:71]
	v_mfma_f32_16x16x32_bf16 v[68:71], v[144:147], v[192:195], v[64:67]
	v_mfma_f32_16x16x32_bf16 v[64:67], v[116:119], v[196:199], v[72:75]
	v_mfma_f32_16x16x32_bf16 v[48:51], v[116:119], v[148:151], v[48:51]
	v_mfma_f32_16x16x32_bf16 v[52:55], v[124:127], v[148:151], v[52:55]
	v_mfma_f32_16x16x32_bf16 v[56:59], v[116:119], v[180:183], v[56:59]
	v_mfma_f32_16x16x32_bf16 v[60:63], v[124:127], v[180:183], v[60:63]
	v_mfma_f32_16x16x32_bf16 v[72:75], v[120:123], v[200:203], v[64:67]
	v_mfma_f32_16x16x32_bf16 v[64:67], v[124:127], v[196:199], v[76:79]
	v_mfma_f32_16x16x32_bf16 v[48:51], v[120:123], v[152:155], v[48:51]
	v_mfma_f32_16x16x32_bf16 v[52:55], v[144:147], v[152:155], v[52:55]
	v_mfma_f32_16x16x32_bf16 v[56:59], v[120:123], v[184:187], v[56:59]
	v_mfma_f32_16x16x32_bf16 v[60:63], v[144:147], v[184:187], v[60:63]
	v_mfma_f32_16x16x32_bf16 v[76:79], v[144:147], v[200:203], v[64:67]
	s_setprio 0
	s_barrier
	s_mov_b32 m0, s47
	v_lshl_add_u64 v[240:241], s[14:15], 0, v[106:107]
	ds_read_b128 v[64:67], v128
	ds_read_b128 v[208:211], v128 offset:1024
	ds_read_b128 v[212:215], v128 offset:2048
	ds_read_b128 v[216:219], v128 offset:3072
	global_load_lds_dwordx4 v[240:241], off
	v_lshl_add_u64 v[232:233], s[14:15], 0, v[104:105]
	s_mov_b32 m0, s13
	s_nop 0
	global_load_lds_dwordx4 v[232:233], off
	s_barrier
	s_waitcnt lgkmcnt(0)
	s_setprio 1
	s_waitcnt lgkmcnt(0)
	v_mfma_f32_16x16x32_bf16 v[16:19], v[212:215], v[148:151], v[16:19]
	v_mfma_f32_16x16x32_bf16 v[96:99], v[64:67], v[148:151], v[96:99]
	v_mfma_f32_16x16x32_bf16 v[148:151], v[216:219], v[152:155], v[16:19]
	v_mfma_f32_16x16x32_bf16 v[16:19], v[64:67], v[180:183], v[20:23]
	v_mfma_f32_16x16x32_bf16 v[20:23], v[208:211], v[184:187], v[16:19]
	v_mfma_f32_16x16x32_bf16 v[16:19], v[212:215], v[180:183], v[24:27]
	v_mfma_f32_16x16x32_bf16 v[24:27], v[216:219], v[184:187], v[16:19]
	v_mfma_f32_16x16x32_bf16 v[16:19], v[64:67], v[188:191], v[28:31]
	v_mfma_f32_16x16x32_bf16 v[28:31], v[208:211], v[192:195], v[16:19]
	v_mfma_f32_16x16x32_bf16 v[16:19], v[212:215], v[188:191], v[32:35]
	v_mfma_f32_16x16x32_bf16 v[220:223], v[208:211], v[152:155], v[96:99]
	v_mfma_f32_16x16x32_bf16 v[152:155], v[216:219], v[192:195], v[16:19]
	v_mfma_f32_16x16x32_bf16 v[16:19], v[64:67], v[196:199], v[36:39]
	v_mfma_f32_16x16x32_bf16 v[180:183], v[208:211], v[200:203], v[16:19]
	v_mfma_f32_16x16x32_bf16 v[16:19], v[212:215], v[196:199], v[40:43]
	v_mfma_f32_16x16x32_bf16 v[40:43], v[216:219], v[200:203], v[16:19]
	s_setprio 0
	s_mov_b32 m0, s16
	v_lshl_add_u64 v[138:139], s[44:45], 0, v[106:107]
	s_barrier
	s_nop 2
	ds_read_b128 v[16:19], v114 offset:16384
	ds_read_b128 v[32:35], v114 offset:17408
	ds_read_b128 v[36:39], v114 offset:18432
	ds_read_b128 v[96:99], v114 offset:19456
	ds_read_b128 v[184:187], v114 offset:20480
	ds_read_b128 v[188:191], v114 offset:21504
	ds_read_b128 v[192:195], v114 offset:22528
	ds_read_b128 v[196:199], v114 offset:23552
	global_load_lds_dwordx4 v[138:139], off
	v_lshl_add_u64 v[140:141], s[44:45], 0, v[104:105]
	s_mov_b32 m0, s17
	s_nop 0
	global_load_lds_dwordx4 v[140:141], off
	s_barrier
	s_waitcnt lgkmcnt(0)
	s_setprio 1
	s_waitcnt lgkmcnt(0)
	v_mfma_f32_16x16x32_bf16 v[0:3], v[116:119], v[192:195], v[0:3]
	v_mfma_f32_16x16x32_bf16 v[156:159], v[116:119], v[16:19], v[156:159]
	v_mfma_f32_16x16x32_bf16 v[160:163], v[124:127], v[16:19], v[160:163]
	v_mfma_f32_16x16x32_bf16 v[164:167], v[116:119], v[36:39], v[164:167]
	v_mfma_f32_16x16x32_bf16 v[168:171], v[124:127], v[36:39], v[168:171]
	v_mfma_f32_16x16x32_bf16 v[172:175], v[116:119], v[184:187], v[172:175]
	v_mfma_f32_16x16x32_bf16 v[176:179], v[124:127], v[184:187], v[176:179]
	v_mfma_f32_16x16x32_bf16 v[116:119], v[120:123], v[196:199], v[0:3]
	v_mfma_f32_16x16x32_bf16 v[0:3], v[124:127], v[192:195], v[4:7]
	v_mfma_f32_16x16x32_bf16 v[156:159], v[120:123], v[32:35], v[156:159]
	v_mfma_f32_16x16x32_bf16 v[160:163], v[144:147], v[32:35], v[160:163]
	v_mfma_f32_16x16x32_bf16 v[164:167], v[120:123], v[96:99], v[164:167]
	v_mfma_f32_16x16x32_bf16 v[168:171], v[144:147], v[96:99], v[168:171]
	v_mfma_f32_16x16x32_bf16 v[172:175], v[120:123], v[188:191], v[172:175]
	v_mfma_f32_16x16x32_bf16 v[176:179], v[144:147], v[188:191], v[176:179]
	v_mfma_f32_16x16x32_bf16 v[120:123], v[144:147], v[196:199], v[0:3]
	s_setprio 0
	s_barrier
	s_add_u32 s40, s14, 0x10000
	s_addc_u32 s41, s15, 0
	s_mov_b32 m0, vcc_lo
	v_lshl_add_u64 v[0:1], s[40:41], 0, v[106:107]
	global_load_lds_dwordx4 v[0:1], off
	v_lshl_add_u64 v[0:1], s[40:41], 0, v[104:105]
	s_mov_b32 m0, s31
	s_nop 0
	global_load_lds_dwordx4 v[0:1], off
	s_waitcnt vmcnt(6)
	s_barrier
	s_setprio 1
	v_mfma_f32_16x16x32_bf16 v[0:3], v[64:67], v[16:19], v[8:11]
	v_mfma_f32_16x16x32_bf16 v[124:127], v[208:211], v[32:35], v[0:3]
	v_mfma_f32_16x16x32_bf16 v[0:3], v[212:215], v[16:19], v[12:15]
	v_mfma_f32_16x16x32_bf16 v[12:15], v[216:219], v[32:35], v[0:3]
	v_mfma_f32_16x16x32_bf16 v[0:3], v[64:67], v[36:39], v[44:47]
	v_mfma_f32_16x16x32_bf16 v[44:47], v[208:211], v[96:99], v[0:3]
	v_mfma_f32_16x16x32_bf16 v[0:3], v[212:215], v[36:39], v[88:91]
	v_mfma_f32_16x16x32_bf16 v[144:147], v[216:219], v[96:99], v[0:3]
	v_mfma_f32_16x16x32_bf16 v[0:3], v[64:67], v[184:187], v[92:95]
	v_mfma_f32_16x16x32_bf16 v[200:203], v[208:211], v[188:191], v[0:3]
	v_mfma_f32_16x16x32_bf16 v[0:3], v[212:215], v[184:187], v[100:103]
	v_mfma_f32_16x16x32_bf16 v[184:187], v[216:219], v[188:191], v[0:3]
	v_mfma_f32_16x16x32_bf16 v[0:3], v[64:67], v[192:195], v[80:83]
	v_mfma_f32_16x16x32_bf16 v[188:191], v[208:211], v[196:199], v[0:3]
	v_mfma_f32_16x16x32_bf16 v[0:3], v[212:215], v[192:195], v[84:87]
	v_mfma_f32_16x16x32_bf16 v[192:195], v[216:219], v[196:199], v[0:3]
	s_setprio 0
	s_barrier
	ds_read_b128 v[8:11], v143
	ds_read_b128 v[92:95], v143 offset:1024
	ds_read_b128 v[196:199], v143 offset:2048
	ds_read_b128 v[208:211], v143 offset:3072
	s_add_u32 s40, s44, 0x10000
	s_addc_u32 s41, s45, 0
	s_mov_b32 m0, s36
	v_lshl_add_u64 v[0:1], s[40:41], 0, v[106:107]
	ds_read_b128 v[4:7], v114 offset:32768
	ds_read_b128 v[36:39], v114 offset:33792
	ds_read_b128 v[88:91], v114 offset:34816
	ds_read_b128 v[212:215], v114 offset:35840
	ds_read_b128 v[216:219], v114 offset:36864
	ds_read_b128 v[224:227], v114 offset:37888
	ds_read_b128 v[228:231], v114 offset:38912
	ds_read_b128 v[244:247], v114 offset:39936
	global_load_lds_dwordx4 v[0:1], off
	v_lshl_add_u64 v[0:1], s[40:41], 0, v[104:105]
	s_mov_b32 m0, s37
	s_nop 0
	global_load_lds_dwordx4 v[0:1], off
	s_waitcnt lgkmcnt(8)
	s_barrier
	s_waitcnt lgkmcnt(0)
	s_setprio 1
	s_waitcnt lgkmcnt(0)
	v_mfma_f32_16x16x32_bf16 v[0:3], v[8:11], v[4:7], v[48:51]
	v_mfma_f32_16x16x32_bf16 v[248:251], v[92:95], v[36:39], v[0:3]
	v_mfma_f32_16x16x32_bf16 v[0:3], v[196:199], v[4:7], v[52:55]
	v_mfma_f32_16x16x32_bf16 v[96:99], v[208:211], v[36:39], v[0:3]
	v_mfma_f32_16x16x32_bf16 v[0:3], v[8:11], v[88:91], v[56:59]
	v_mfma_f32_16x16x32_bf16 v[80:83], v[92:95], v[212:215], v[0:3]
	v_mfma_f32_16x16x32_bf16 v[0:3], v[196:199], v[88:91], v[60:63]
	v_mfma_f32_16x16x32_bf16 v[64:67], v[208:211], v[212:215], v[0:3]
	v_mfma_f32_16x16x32_bf16 v[0:3], v[8:11], v[216:219], v[204:207]
	v_mfma_f32_16x16x32_bf16 v[48:51], v[92:95], v[224:227], v[0:3]
	v_mfma_f32_16x16x32_bf16 v[0:3], v[196:199], v[216:219], v[68:71]
	v_mfma_f32_16x16x32_bf16 v[32:35], v[208:211], v[224:227], v[0:3]
	v_mfma_f32_16x16x32_bf16 v[0:3], v[8:11], v[228:231], v[72:75]
	v_mfma_f32_16x16x32_bf16 v[16:19], v[92:95], v[244:247], v[0:3]
	v_mfma_f32_16x16x32_bf16 v[0:3], v[196:199], v[228:231], v[76:79]
	v_mfma_f32_16x16x32_bf16 v[0:3], v[208:211], v[244:247], v[0:3]
	s_setprio 0
	s_barrier
	s_mov_b32 m0, s48
	v_lshl_add_u64 v[52:53], v[240:241], 0, s[28:29]
	ds_read_b128 v[204:207], v242
	ds_read_b128 v[236:239], v242 offset:1024
	ds_read_b128 v[130:133], v242 offset:2048
	ds_read_b128 v[134:137], v242 offset:3072
	global_load_lds_dwordx4 v[52:53], off
	v_lshl_add_u64 v[52:53], v[232:233], 0, s[28:29]
	s_mov_b32 m0, vcc_hi
	s_nop 0
	global_load_lds_dwordx4 v[52:53], off
	s_barrier
	s_waitcnt lgkmcnt(0)
	s_setprio 1
	s_waitcnt lgkmcnt(0)
	v_mfma_f32_16x16x32_bf16 v[52:55], v[204:207], v[4:7], v[220:223]
	v_mfma_f32_16x16x32_bf16 v[4:7], v[130:133], v[4:7], v[148:151]
	v_mfma_f32_16x16x32_bf16 v[100:103], v[134:137], v[36:39], v[4:7]
	v_mfma_f32_16x16x32_bf16 v[4:7], v[204:207], v[88:91], v[20:23]
	v_mfma_f32_16x16x32_bf16 v[84:87], v[236:239], v[212:215], v[4:7]
	v_mfma_f32_16x16x32_bf16 v[4:7], v[130:133], v[88:91], v[24:27]
	v_mfma_f32_16x16x32_bf16 v[68:71], v[134:137], v[212:215], v[4:7]
	v_mfma_f32_16x16x32_bf16 v[4:7], v[204:207], v[216:219], v[28:31]
	v_mfma_f32_16x16x32_bf16 v[220:223], v[236:239], v[36:39], v[52:55]
	v_mfma_f32_16x16x32_bf16 v[52:55], v[236:239], v[224:227], v[4:7]
	v_mfma_f32_16x16x32_bf16 v[4:7], v[130:133], v[216:219], v[152:155]
	v_mfma_f32_16x16x32_bf16 v[36:39], v[134:137], v[224:227], v[4:7]
	v_mfma_f32_16x16x32_bf16 v[4:7], v[204:207], v[228:231], v[180:183]
	v_mfma_f32_16x16x32_bf16 v[20:23], v[236:239], v[244:247], v[4:7]
	v_mfma_f32_16x16x32_bf16 v[4:7], v[130:133], v[228:231], v[40:43]
	v_mfma_f32_16x16x32_bf16 v[4:7], v[134:137], v[244:247], v[4:7]
	s_setprio 0
	s_mov_b32 m0, s24
	v_lshl_add_u64 v[24:25], v[138:139], 0, s[28:29]
	s_barrier
	ds_read_b128 v[28:31], v114 offset:49152
	ds_read_b128 v[60:63], v114 offset:50176
	ds_read_b128 v[76:79], v114 offset:51200
	ds_read_b128 v[148:151], v114 offset:52224
	ds_read_b128 v[152:155], v114 offset:53248
	ds_read_b128 v[180:183], v114 offset:54272
	ds_read_b128 v[212:215], v114 offset:55296
	ds_read_b128 v[216:219], v114 offset:56320
	global_load_lds_dwordx4 v[24:25], off
	v_lshl_add_u64 v[24:25], v[140:141], 0, s[28:29]
	s_mov_b32 m0, s25
	s_nop 0
	global_load_lds_dwordx4 v[24:25], off
	s_barrier
	s_waitcnt lgkmcnt(0)
	s_setprio 1
	s_waitcnt lgkmcnt(0)
	v_mfma_f32_16x16x32_bf16 v[24:27], v[8:11], v[28:31], v[156:159]
	v_mfma_f32_16x16x32_bf16 v[156:159], v[92:95], v[60:63], v[24:27]
	v_mfma_f32_16x16x32_bf16 v[24:27], v[196:199], v[28:31], v[160:163]
	v_mfma_f32_16x16x32_bf16 v[160:163], v[208:211], v[60:63], v[24:27]
	v_mfma_f32_16x16x32_bf16 v[24:27], v[8:11], v[76:79], v[164:167]
	v_mfma_f32_16x16x32_bf16 v[88:91], v[92:95], v[148:151], v[24:27]
	v_mfma_f32_16x16x32_bf16 v[24:27], v[196:199], v[76:79], v[168:171]
	v_mfma_f32_16x16x32_bf16 v[72:75], v[208:211], v[148:151], v[24:27]
	v_mfma_f32_16x16x32_bf16 v[24:27], v[8:11], v[152:155], v[172:175]
	v_mfma_f32_16x16x32_bf16 v[56:59], v[92:95], v[180:183], v[24:27]
	v_mfma_f32_16x16x32_bf16 v[24:27], v[196:199], v[152:155], v[176:179]
	v_mfma_f32_16x16x32_bf16 v[8:11], v[8:11], v[212:215], v[116:119]
	v_mfma_f32_16x16x32_bf16 v[40:43], v[208:211], v[180:183], v[24:27]
	v_mfma_f32_16x16x32_bf16 v[24:27], v[92:95], v[216:219], v[8:11]
	v_mfma_f32_16x16x32_bf16 v[8:11], v[196:199], v[212:215], v[120:123]
	v_mfma_f32_16x16x32_bf16 v[8:11], v[208:211], v[216:219], v[8:11]
	s_setprio 0
	s_barrier
	s_add_u32 s14, s14, 0x10080
	s_addc_u32 s15, s15, 0
	s_mov_b32 m0, s42
	v_lshl_add_u64 v[92:93], s[14:15], 0, v[106:107]
	global_load_lds_dwordx4 v[92:93], off
	v_lshl_add_u64 v[92:93], s[14:15], 0, v[104:105]
	s_mov_b32 m0, s20
	s_nop 0
	global_load_lds_dwordx4 v[92:93], off
	s_waitcnt vmcnt(6)
	s_barrier
	s_setprio 1
	v_mfma_f32_16x16x32_bf16 v[12:15], v[130:133], v[28:31], v[12:15]
	v_mfma_f32_16x16x32_bf16 v[92:95], v[204:207], v[28:31], v[124:127]
	v_mfma_f32_16x16x32_bf16 v[120:123], v[134:137], v[60:63], v[12:15]
	v_mfma_f32_16x16x32_bf16 v[12:15], v[204:207], v[76:79], v[44:47]
	v_mfma_f32_16x16x32_bf16 v[116:119], v[236:239], v[60:63], v[92:95]
	v_mfma_f32_16x16x32_bf16 v[92:95], v[236:239], v[148:151], v[12:15]
	v_mfma_f32_16x16x32_bf16 v[12:15], v[130:133], v[76:79], v[144:147]
	v_mfma_f32_16x16x32_bf16 v[76:79], v[134:137], v[148:151], v[12:15]
	v_mfma_f32_16x16x32_bf16 v[12:15], v[204:207], v[152:155], v[200:203]
	v_mfma_f32_16x16x32_bf16 v[60:63], v[236:239], v[180:183], v[12:15]
	v_mfma_f32_16x16x32_bf16 v[12:15], v[130:133], v[152:155], v[184:187]
	v_mfma_f32_16x16x32_bf16 v[44:47], v[134:137], v[180:183], v[12:15]
	v_mfma_f32_16x16x32_bf16 v[12:15], v[204:207], v[212:215], v[188:191]
	v_mfma_f32_16x16x32_bf16 v[28:31], v[236:239], v[216:219], v[12:15]
	v_mfma_f32_16x16x32_bf16 v[12:15], v[130:133], v[212:215], v[192:195]
	v_mfma_f32_16x16x32_bf16 v[12:15], v[134:137], v[216:219], v[12:15]
	s_branch .Lfa1_x
	s_nop 0
	s_nop 0
	s_nop 0
	s_nop 0
	s_nop 0
	s_nop 0
	s_nop 0
	s_nop 0
	s_nop 0
	s_nop 0
	s_nop 0
	s_nop 0
	s_nop 0
	s_nop 0
	s_nop 0
	s_nop 0
	s_nop 0
	s_nop 0
	s_nop 0
	s_nop 0
.Lfa1_xd:
	v_or_b32_e32 v128, v128, v110
	v_pk_fma_f32 v[136:137], v[248:249], v[124:125], v[136:137]
	v_pk_fma_f32 v[138:139], v[250:251], v[132:133], v[138:139]
	v_readlane_b32 s54, v252, 6
	v_readlane_b32 s55, v252, 7
	v_cvt_pk_bf16_f32 v164, v136, v137
	v_cvt_pk_bf16_f32 v165, v138, v139
	v_lshl_add_u64 v[138:139], v[128:129], 1, s[54:55]
	v_pk_mul_f32 v[136:137], v[248:249], v[126:127]
	v_pk_mul_f32 v[140:141], v[250:251], v[134:135]
	v_pk_fma_f32 v[136:137], v[156:157], v[124:125], v[136:137] neg_lo:[0,0,1] neg_hi:[0,0,1]
	v_pk_fma_f32 v[140:141], v[158:159], v[132:133], v[140:141] neg_lo:[0,0,1] neg_hi:[0,0,1]
	v_cvt_pk_bf16_f32 v168, v136, v137
	v_cvt_pk_bf16_f32 v169, v140, v141
	v_pk_mul_f32 v[136:137], v[116:117], v[126:127]
	v_pk_mul_f32 v[126:127], v[220:221], v[126:127]
	v_pk_fma_f32 v[136:137], v[220:221], v[124:125], v[136:137]
	v_pk_mul_f32 v[140:141], v[118:119], v[134:135]
	v_pk_fma_f32 v[116:117], v[116:117], v[124:125], v[126:127] neg_lo:[0,0,1] neg_hi:[0,0,1]
	v_pk_mul_f32 v[124:125], v[222:223], v[134:135]
	v_pk_fma_f32 v[140:141], v[222:223], v[132:133], v[140:141]
	v_pk_fma_f32 v[118:119], v[118:119], v[132:133], v[124:125] neg_lo:[0,0,1] neg_hi:[0,0,1]
	v_cvt_pk_bf16_f32 v172, v136, v137
	v_cvt_pk_bf16_f32 v173, v140, v141
	v_cvt_pk_bf16_f32 v176, v116, v117
	v_cvt_pk_bf16_f32 v177, v118, v119
	v_readlane_b32 s49, v252, 1
	v_readlane_b32 s50, v252, 2
	v_readlane_b32 s51, v252, 3
	v_readlane_b32 s52, v252, 4
	v_readlane_b32 s53, v252, 5
	v_mad_u64_u32 v[116:117], s[14:15], v115, 13, v[130:131]
	v_cvt_f32_i32_e32 v117, v116
	v_add_u32_e32 v119, v116, v115
	v_cvt_f32_i32_e32 v124, v119
	v_mul_f32_e32 v116, 0x39c90fdb, v117
	v_mul_f32_e32 v117, 0.15915494, v116
	v_cos_f32_e32 v116, v117
	v_sin_f32_e32 v118, v117
	v_mul_f32_e32 v117, 0x39c90fdb, v124
	v_add_u32_e32 v124, v119, v115
	v_add_u32_e32 v115, v124, v115
	v_cvt_f32_i32_e32 v125, v124
	v_cvt_f32_i32_e32 v115, v115
	v_mul_f32_e32 v119, 0.15915494, v117
	v_cos_f32_e32 v117, v119
	v_mul_f32_e32 v125, 0x39c90fdb, v125
	v_mul_f32_e32 v115, 0x39c90fdb, v115
	v_mul_f32_e32 v125, 0.15915494, v125
	v_mul_f32_e32 v115, 0.15915494, v115
	v_sin_f32_e32 v119, v119
	v_sin_f32_e32 v126, v125
	v_sin_f32_e32 v127, v115
	v_cos_f32_e32 v124, v125
	v_cos_f32_e32 v125, v115
	v_pk_mul_f32 v[130:131], v[160:161], v[118:119]
	v_pk_mul_f32 v[132:133], v[162:163], v[126:127]
	v_pk_fma_f32 v[130:131], v[96:97], v[116:117], v[130:131]
	v_pk_fma_f32 v[132:133], v[98:99], v[124:125], v[132:133]
	v_pk_mul_f32 v[96:97], v[96:97], v[118:119]
	v_pk_mul_f32 v[98:99], v[98:99], v[126:127]
	v_pk_fma_f32 v[96:97], v[160:161], v[116:117], v[96:97] neg_lo:[0,0,1] neg_hi:[0,0,1]
	v_pk_fma_f32 v[98:99], v[162:163], v[124:125], v[98:99] neg_lo:[0,0,1] neg_hi:[0,0,1]
	v_cvt_pk_bf16_f32 v170, v96, v97
	v_cvt_pk_bf16_f32 v171, v98, v99
	v_lshl_add_u64 v[138:139], v[138:139], 0, v[196:197]
	s_nop 0
	v_permlane16_swap_b32_e32 v168, v170
	v_permlane16_swap_b32_e32 v169, v171
	global_store_dwordx4 v[138:139], v[168:171], off offset:256
	v_pk_mul_f32 v[96:97], v[120:121], v[118:119]
	v_pk_mul_f32 v[98:99], v[122:123], v[126:127]
	v_pk_fma_f32 v[96:97], v[100:101], v[116:117], v[96:97]
	v_pk_fma_f32 v[98:99], v[102:103], v[124:125], v[98:99]
	v_cvt_pk_bf16_f32 v174, v96, v97
	v_cvt_pk_bf16_f32 v175, v98, v99
	s_nop 1
	v_permlane16_swap_b32_e32 v172, v174
	v_permlane16_swap_b32_e32 v173, v175
	global_store_dwordx4 v[138:139], v[172:175], off offset:512
	v_pk_mul_f32 v[96:97], v[100:101], v[118:119]
	v_pk_mul_f32 v[98:99], v[102:103], v[126:127]
	v_pk_fma_f32 v[96:97], v[120:121], v[116:117], v[96:97] neg_lo:[0,0,1] neg_hi:[0,0,1]
	v_pk_fma_f32 v[98:99], v[122:123], v[124:125], v[98:99] neg_lo:[0,0,1] neg_hi:[0,0,1]
	v_cvt_pk_bf16_f32 v166, v130, v131
	v_cvt_pk_bf16_f32 v167, v132, v133
	v_cvt_pk_bf16_f32 v178, v96, v97
	v_cvt_pk_bf16_f32 v179, v98, v99
	s_nop 1
	v_permlane16_swap_b32_e32 v164, v166
	v_permlane16_swap_b32_e32 v165, v167
	global_store_dwordx4 v[138:139], v[164:167], off
	v_permlane16_swap_b32_e32 v176, v178
	v_permlane16_swap_b32_e32 v177, v179
	global_store_dwordx4 v[138:139], v[176:179], off offset:768
	v_or_b32_e32 v101, 16, v108
	s_nop 0
	v_mul_lo_u32 v96, v101, v110
	v_cvt_f32_i32_e32 v97, v96
	v_add_u32_e32 v99, v96, v101
	v_cvt_f32_i32_e32 v100, v99
	v_lshl_add_u32 v115, v101, 18, s0
	v_mul_f32_e32 v96, 0x39c90fdb, v97
	v_mul_f32_e32 v97, 0.15915494, v96
	v_cos_f32_e32 v96, v97
	v_sin_f32_e32 v98, v97
	v_mul_f32_e32 v97, 0x39c90fdb, v100
	v_add_u32_e32 v100, v99, v101
	v_cvt_f32_i32_e32 v102, v100
	v_add_u32_e32 v100, v100, v101
	v_cvt_f32_i32_e32 v103, v100
	v_mul_f32_e32 v99, 0.15915494, v97
	v_mul_f32_e32 v102, 0x39c90fdb, v102
	v_mul_f32_e32 v116, 0.15915494, v102
	v_mul_f32_e32 v103, 0x39c90fdb, v103
	v_mul_f32_e32 v117, 0.15915494, v103
	v_cos_f32_e32 v97, v99
	v_sin_f32_e32 v99, v99
	v_cos_f32_e32 v102, v116
	v_sin_f32_e32 v116, v116
	v_cos_f32_e32 v103, v117
	v_sin_f32_e32 v117, v117
	v_pk_mul_f32 v[118:119], v[88:89], v[98:99]
	v_or_b32_e32 v128, v115, v110
	v_pk_fma_f32 v[118:119], v[80:81], v[96:97], v[118:119]
	v_pk_mul_f32 v[120:121], v[90:91], v[116:117]
	v_pk_mul_f32 v[80:81], v[80:81], v[98:99]
	v_pk_fma_f32 v[120:121], v[82:83], v[102:103], v[120:121]
	v_pk_mul_f32 v[82:83], v[82:83], v[116:117]
	v_pk_fma_f32 v[80:81], v[88:89], v[96:97], v[80:81] neg_lo:[0,0,1] neg_hi:[0,0,1]
	v_pk_fma_f32 v[82:83], v[90:91], v[102:103], v[82:83] neg_lo:[0,0,1] neg_hi:[0,0,1]
	v_cvt_pk_bf16_f32 v172, v118, v119
	v_cvt_pk_bf16_f32 v173, v120, v121
	v_lshl_add_u64 v[120:121], v[128:129], 1, s[54:55]
	v_cvt_pk_bf16_f32 v164, v80, v81
	v_cvt_pk_bf16_f32 v165, v82, v83
	v_pk_mul_f32 v[80:81], v[92:93], v[98:99]
	v_pk_mul_f32 v[82:83], v[94:95], v[116:117]
	v_pk_fma_f32 v[80:81], v[84:85], v[96:97], v[80:81]
	v_pk_fma_f32 v[82:83], v[86:87], v[102:103], v[82:83]
	v_cvt_pk_bf16_f32 v168, v80, v81
	v_cvt_pk_bf16_f32 v169, v82, v83
	v_pk_mul_f32 v[80:81], v[84:85], v[98:99]
	v_pk_mul_f32 v[82:83], v[86:87], v[116:117]
	v_pk_fma_f32 v[80:81], v[92:93], v[96:97], v[80:81] neg_lo:[0,0,1] neg_hi:[0,0,1]
	v_pk_fma_f32 v[82:83], v[94:95], v[102:103], v[82:83] neg_lo:[0,0,1] neg_hi:[0,0,1]
	v_cvt_pk_bf16_f32 v176, v80, v81
	v_cvt_pk_bf16_f32 v177, v82, v83
	v_mad_u64_u32 v[80:81], s[14:15], v101, 13, v[100:101]
	v_cvt_f32_i32_e32 v81, v80
	v_add_u32_e32 v83, v80, v101
	v_cvt_f32_i32_e32 v84, v83
	v_mul_f32_e32 v80, 0x39c90fdb, v81
	v_mul_f32_e32 v81, 0.15915494, v80
	v_cos_f32_e32 v80, v81
	v_sin_f32_e32 v82, v81
	v_mul_f32_e32 v81, 0x39c90fdb, v84
	v_add_u32_e32 v84, v83, v101
	v_cvt_f32_i32_e32 v85, v84
	v_add_u32_e32 v84, v84, v101
	v_cvt_f32_i32_e32 v87, v84
	v_mul_f32_e32 v83, 0.15915494, v81
	v_mul_f32_e32 v85, 0x39c90fdb, v85
	v_mul_f32_e32 v85, 0.15915494, v85
	v_cos_f32_e32 v84, v85
	v_sin_f32_e32 v86, v85
	v_mul_f32_e32 v85, 0x39c90fdb, v87
	v_mul_f32_e32 v87, 0.15915494, v85
	v_cos_f32_e32 v81, v83
	v_sin_f32_e32 v83, v83
	v_cos_f32_e32 v85, v87
	v_sin_f32_e32 v87, v87
	v_pk_mul_f32 v[88:89], v[72:73], v[82:83]
	s_nop 0
	v_pk_fma_f32 v[88:89], v[64:65], v[80:81], v[88:89]
	v_pk_mul_f32 v[90:91], v[74:75], v[86:87]
	v_pk_mul_f32 v[64:65], v[64:65], v[82:83]
	v_pk_fma_f32 v[90:91], v[66:67], v[84:85], v[90:91]
	v_pk_mul_f32 v[66:67], v[66:67], v[86:87]
	v_pk_fma_f32 v[64:65], v[72:73], v[80:81], v[64:65] neg_lo:[0,0,1] neg_hi:[0,0,1]
	v_pk_fma_f32 v[66:67], v[74:75], v[84:85], v[66:67] neg_lo:[0,0,1] neg_hi:[0,0,1]
	v_cvt_pk_bf16_f32 v166, v64, v65
	v_cvt_pk_bf16_f32 v167, v66, v67
	v_lshl_add_u64 v[120:121], v[120:121], 0, v[196:197]
	s_nop 0
	v_permlane16_swap_b32_e32 v164, v166
	v_permlane16_swap_b32_e32 v165, v167
	global_store_dwordx4 v[120:121], v[164:167], off offset:256
	v_pk_mul_f32 v[64:65], v[76:77], v[82:83]
	v_pk_mul_f32 v[66:67], v[78:79], v[86:87]
	v_pk_fma_f32 v[64:65], v[68:69], v[80:81], v[64:65]
	v_pk_fma_f32 v[66:67], v[70:71], v[84:85], v[66:67]
	v_cvt_pk_bf16_f32 v170, v64, v65
	v_cvt_pk_bf16_f32 v171, v66, v67
	s_nop 1
	v_permlane16_swap_b32_e32 v168, v170
	v_permlane16_swap_b32_e32 v169, v171
	global_store_dwordx4 v[120:121], v[168:171], off offset:512
	v_pk_mul_f32 v[64:65], v[68:69], v[82:83]
	v_pk_mul_f32 v[66:67], v[70:71], v[86:87]
	v_pk_fma_f32 v[64:65], v[76:77], v[80:81], v[64:65] neg_lo:[0,0,1] neg_hi:[0,0,1]
	v_pk_fma_f32 v[66:67], v[78:79], v[84:85], v[66:67] neg_lo:[0,0,1] neg_hi:[0,0,1]
	v_cvt_pk_bf16_f32 v174, v88, v89
	v_cvt_pk_bf16_f32 v175, v90, v91
	v_cvt_pk_bf16_f32 v178, v64, v65
	v_cvt_pk_bf16_f32 v179, v66, v67
	s_nop 1
	v_permlane16_swap_b32_e32 v172, v174
	v_permlane16_swap_b32_e32 v173, v175
	global_store_dwordx4 v[120:121], v[172:175], off
	v_permlane16_swap_b32_e32 v176, v178
	v_permlane16_swap_b32_e32 v177, v179
	global_store_dwordx4 v[120:121], v[176:179], off offset:768
	v_or_b32_e32 v69, 32, v108
	s_nop 0
	v_mul_lo_u32 v64, v69, v110
	v_cvt_f32_i32_e32 v65, v64
	v_add_u32_e32 v67, v64, v69
	v_cvt_f32_i32_e32 v68, v67
	v_lshl_add_u32 v74, v69, 18, s0
	v_mul_f32_e32 v64, 0x39c90fdb, v65
	v_mul_f32_e32 v65, 0.15915494, v64
	v_cos_f32_e32 v64, v65
	v_sin_f32_e32 v66, v65
	v_mul_f32_e32 v65, 0x39c90fdb, v68
	v_add_u32_e32 v68, v67, v69
	v_cvt_f32_i32_e32 v70, v68
	v_add_u32_e32 v68, v68, v69
	v_cvt_f32_i32_e32 v71, v68
	v_mul_f32_e32 v67, 0.15915494, v65
	v_mul_f32_e32 v70, 0x39c90fdb, v70
	v_mul_f32_e32 v72, 0.15915494, v70
	v_mul_f32_e32 v71, 0x39c90fdb, v71
	v_mul_f32_e32 v73, 0.15915494, v71
	v_cos_f32_e32 v65, v67
	v_sin_f32_e32 v67, v67
	v_cos_f32_e32 v70, v72
	v_sin_f32_e32 v72, v72
	v_cos_f32_e32 v71, v73
	v_sin_f32_e32 v73, v73
	v_or_b32_e32 v128, v74, v110
	v_pk_mul_f32 v[74:75], v[56:57], v[66:67]
	v_pk_mul_f32 v[76:77], v[58:59], v[72:73]
	v_pk_fma_f32 v[74:75], v[48:49], v[64:65], v[74:75]
	v_pk_fma_f32 v[76:77], v[50:51], v[70:71], v[76:77]
	v_pk_mul_f32 v[48:49], v[48:49], v[66:67]
	v_pk_mul_f32 v[50:51], v[50:51], v[72:73]
	v_pk_fma_f32 v[48:49], v[56:57], v[64:65], v[48:49] neg_lo:[0,0,1] neg_hi:[0,0,1]
	v_pk_fma_f32 v[50:51], v[58:59], v[70:71], v[50:51] neg_lo:[0,0,1] neg_hi:[0,0,1]
	v_cvt_pk_bf16_f32 v172, v74, v75
	v_cvt_pk_bf16_f32 v173, v76, v77
	v_lshl_add_u64 v[76:77], v[128:129], 1, s[54:55]
	v_cvt_pk_bf16_f32 v164, v48, v49
	v_cvt_pk_bf16_f32 v165, v50, v51
	v_pk_mul_f32 v[48:49], v[60:61], v[66:67]
	v_pk_mul_f32 v[50:51], v[62:63], v[72:73]
	v_pk_fma_f32 v[48:49], v[52:53], v[64:65], v[48:49]
	v_pk_fma_f32 v[50:51], v[54:55], v[70:71], v[50:51]
	v_cvt_pk_bf16_f32 v168, v48, v49
	v_cvt_pk_bf16_f32 v169, v50, v51
	v_pk_mul_f32 v[48:49], v[52:53], v[66:67]
	v_pk_mul_f32 v[50:51], v[54:55], v[72:73]
	v_pk_fma_f32 v[48:49], v[60:61], v[64:65], v[48:49] neg_lo:[0,0,1] neg_hi:[0,0,1]
	v_pk_fma_f32 v[50:51], v[62:63], v[70:71], v[50:51] neg_lo:[0,0,1] neg_hi:[0,0,1]
	v_cvt_pk_bf16_f32 v176, v48, v49
	v_cvt_pk_bf16_f32 v177, v50, v51
	v_mad_u64_u32 v[48:49], s[14:15], v69, 13, v[68:69]
	v_cvt_f32_i32_e32 v49, v48
	v_add_u32_e32 v51, v48, v69
	v_cvt_f32_i32_e32 v52, v51
	v_mul_f32_e32 v48, 0x39c90fdb, v49
	v_mul_f32_e32 v49, 0.15915494, v48
	v_cos_f32_e32 v48, v49
	v_sin_f32_e32 v50, v49
	v_mul_f32_e32 v49, 0x39c90fdb, v52
	v_add_u32_e32 v52, v51, v69
	v_cvt_f32_i32_e32 v53, v52
	v_add_u32_e32 v52, v52, v69
	v_cvt_f32_i32_e32 v55, v52
	v_mul_f32_e32 v51, 0.15915494, v49
	v_mul_f32_e32 v53, 0x39c90fdb, v53
	v_mul_f32_e32 v53, 0.15915494, v53
	v_cos_f32_e32 v52, v53
	v_sin_f32_e32 v54, v53
	v_mul_f32_e32 v53, 0x39c90fdb, v55
	v_mul_f32_e32 v55, 0.15915494, v53
	v_cos_f32_e32 v49, v51
	v_sin_f32_e32 v51, v51
	v_cos_f32_e32 v53, v55
	v_sin_f32_e32 v55, v55
	v_pk_mul_f32 v[56:57], v[40:41], v[50:51]
	s_nop 0
	v_pk_fma_f32 v[56:57], v[32:33], v[48:49], v[56:57]
	v_pk_mul_f32 v[58:59], v[42:43], v[54:55]
	v_pk_mul_f32 v[32:33], v[32:33], v[50:51]
	v_pk_fma_f32 v[58:59], v[34:35], v[52:53], v[58:59]
	v_pk_mul_f32 v[34:35], v[34:35], v[54:55]
	v_pk_fma_f32 v[32:33], v[40:41], v[48:49], v[32:33] neg_lo:[0,0,1] neg_hi:[0,0,1]
	v_pk_fma_f32 v[34:35], v[42:43], v[52:53], v[34:35] neg_lo:[0,0,1] neg_hi:[0,0,1]
	v_cvt_pk_bf16_f32 v166, v32, v33
	v_cvt_pk_bf16_f32 v167, v34, v35
	v_lshl_add_u64 v[76:77], v[76:77], 0, v[196:197]
	s_nop 0
	v_permlane16_swap_b32_e32 v164, v166
	v_permlane16_swap_b32_e32 v165, v167
	global_store_dwordx4 v[76:77], v[164:167], off offset:256
	v_pk_mul_f32 v[32:33], v[44:45], v[50:51]
	v_pk_mul_f32 v[34:35], v[46:47], v[54:55]
	v_pk_fma_f32 v[32:33], v[36:37], v[48:49], v[32:33]
	v_pk_fma_f32 v[34:35], v[38:39], v[52:53], v[34:35]
	v_cvt_pk_bf16_f32 v170, v32, v33
	v_cvt_pk_bf16_f32 v171, v34, v35
	s_nop 1
	v_permlane16_swap_b32_e32 v168, v170
	v_permlane16_swap_b32_e32 v169, v171
	global_store_dwordx4 v[76:77], v[168:171], off offset:512
	v_pk_mul_f32 v[32:33], v[36:37], v[50:51]
	v_pk_mul_f32 v[34:35], v[38:39], v[54:55]
	v_pk_fma_f32 v[32:33], v[44:45], v[48:49], v[32:33] neg_lo:[0,0,1] neg_hi:[0,0,1]
	v_pk_fma_f32 v[34:35], v[46:47], v[52:53], v[34:35] neg_lo:[0,0,1] neg_hi:[0,0,1]
	v_cvt_pk_bf16_f32 v174, v56, v57
	v_cvt_pk_bf16_f32 v175, v58, v59
	v_cvt_pk_bf16_f32 v178, v32, v33
	v_cvt_pk_bf16_f32 v179, v34, v35
	s_nop 1
	v_permlane16_swap_b32_e32 v172, v174
	v_permlane16_swap_b32_e32 v173, v175
	global_store_dwordx4 v[76:77], v[172:175], off
	v_permlane16_swap_b32_e32 v176, v178
	v_permlane16_swap_b32_e32 v177, v179
	global_store_dwordx4 v[76:77], v[176:179], off offset:768
	v_or_b32_e32 v37, 48, v108
	s_nop 0
	v_mul_lo_u32 v32, v37, v110
	v_cvt_f32_i32_e32 v33, v32
	v_add_u32_e32 v35, v32, v37
	v_cvt_f32_i32_e32 v36, v35
	v_lshl_add_u32 v42, v37, 18, s0
	v_mul_f32_e32 v32, 0x39c90fdb, v33
	v_mul_f32_e32 v33, 0.15915494, v32
	v_cos_f32_e32 v32, v33
	v_sin_f32_e32 v34, v33
	v_mul_f32_e32 v33, 0x39c90fdb, v36
	v_add_u32_e32 v36, v35, v37
	v_cvt_f32_i32_e32 v38, v36
	v_add_u32_e32 v36, v36, v37
	v_cvt_f32_i32_e32 v39, v36
	v_mul_f32_e32 v35, 0.15915494, v33
	v_mul_f32_e32 v38, 0x39c90fdb, v38
	v_mul_f32_e32 v40, 0.15915494, v38
	v_mul_f32_e32 v39, 0x39c90fdb, v39
	v_mul_f32_e32 v41, 0.15915494, v39
	v_cos_f32_e32 v33, v35
	v_sin_f32_e32 v35, v35
	v_cos_f32_e32 v38, v40
	v_sin_f32_e32 v40, v40
	v_cos_f32_e32 v39, v41
	v_sin_f32_e32 v41, v41
	v_or_b32_e32 v128, v42, v110
	v_pk_mul_f32 v[42:43], v[24:25], v[34:35]
	v_pk_mul_f32 v[44:45], v[26:27], v[40:41]
	v_pk_fma_f32 v[42:43], v[16:17], v[32:33], v[42:43]
	v_pk_fma_f32 v[44:45], v[18:19], v[38:39], v[44:45]
	v_pk_mul_f32 v[16:17], v[16:17], v[34:35]
	v_pk_mul_f32 v[18:19], v[18:19], v[40:41]
	v_pk_fma_f32 v[16:17], v[24:25], v[32:33], v[16:17] neg_lo:[0,0,1] neg_hi:[0,0,1]
	v_pk_fma_f32 v[18:19], v[26:27], v[38:39], v[18:19] neg_lo:[0,0,1] neg_hi:[0,0,1]
	v_cvt_pk_bf16_f32 v172, v42, v43
	v_cvt_pk_bf16_f32 v173, v44, v45
	v_lshl_add_u64 v[44:45], v[128:129], 1, s[54:55]
	v_cvt_pk_bf16_f32 v164, v16, v17
	v_cvt_pk_bf16_f32 v165, v18, v19
	v_pk_mul_f32 v[16:17], v[28:29], v[34:35]
	v_pk_mul_f32 v[18:19], v[30:31], v[40:41]
	v_pk_fma_f32 v[16:17], v[20:21], v[32:33], v[16:17]
	v_pk_fma_f32 v[18:19], v[22:23], v[38:39], v[18:19]
	v_cvt_pk_bf16_f32 v168, v16, v17
	v_cvt_pk_bf16_f32 v169, v18, v19
	v_pk_mul_f32 v[16:17], v[20:21], v[34:35]
	v_pk_mul_f32 v[18:19], v[22:23], v[40:41]
	v_pk_fma_f32 v[16:17], v[28:29], v[32:33], v[16:17] neg_lo:[0,0,1] neg_hi:[0,0,1]
	v_pk_fma_f32 v[18:19], v[30:31], v[38:39], v[18:19] neg_lo:[0,0,1] neg_hi:[0,0,1]
	v_cvt_pk_bf16_f32 v176, v16, v17
	v_cvt_pk_bf16_f32 v177, v18, v19
	v_mad_u64_u32 v[16:17], s[0:1], v37, 13, v[36:37]
	v_cvt_f32_i32_e32 v17, v16
	v_add_u32_e32 v19, v16, v37
	v_cvt_f32_i32_e32 v20, v19
	v_mul_f32_e32 v16, 0x39c90fdb, v17
	v_mul_f32_e32 v17, 0.15915494, v16
	v_cos_f32_e32 v16, v17
	v_sin_f32_e32 v18, v17
	v_mul_f32_e32 v17, 0x39c90fdb, v20
	v_add_u32_e32 v20, v19, v37
	v_cvt_f32_i32_e32 v21, v20
	v_add_u32_e32 v20, v20, v37
	v_cvt_f32_i32_e32 v23, v20
	v_mul_f32_e32 v19, 0.15915494, v17
	v_mul_f32_e32 v21, 0x39c90fdb, v21
	v_mul_f32_e32 v21, 0.15915494, v21
	v_cos_f32_e32 v20, v21
	v_sin_f32_e32 v22, v21
	v_mul_f32_e32 v21, 0x39c90fdb, v23
	v_mul_f32_e32 v23, 0.15915494, v21
	v_cos_f32_e32 v17, v19
	v_sin_f32_e32 v19, v19
	v_cos_f32_e32 v21, v23
	v_sin_f32_e32 v23, v23
	v_pk_mul_f32 v[24:25], v[8:9], v[18:19]
	s_nop 0
	v_pk_fma_f32 v[24:25], v[0:1], v[16:17], v[24:25]
	v_pk_mul_f32 v[26:27], v[10:11], v[22:23]
	v_pk_mul_f32 v[0:1], v[0:1], v[18:19]
	v_pk_fma_f32 v[26:27], v[2:3], v[20:21], v[26:27]
	v_pk_mul_f32 v[2:3], v[2:3], v[22:23]
	v_pk_fma_f32 v[0:1], v[8:9], v[16:17], v[0:1] neg_lo:[0,0,1] neg_hi:[0,0,1]
	v_pk_fma_f32 v[2:3], v[10:11], v[20:21], v[2:3] neg_lo:[0,0,1] neg_hi:[0,0,1]
	v_cvt_pk_bf16_f32 v166, v0, v1
	v_cvt_pk_bf16_f32 v167, v2, v3
	v_lshl_add_u64 v[44:45], v[44:45], 0, v[196:197]
	s_nop 0
	v_permlane16_swap_b32_e32 v164, v166
	v_permlane16_swap_b32_e32 v165, v167
	global_store_dwordx4 v[44:45], v[164:167], off offset:256
	v_pk_mul_f32 v[0:1], v[12:13], v[18:19]
	v_pk_mul_f32 v[2:3], v[14:15], v[22:23]
	v_pk_fma_f32 v[0:1], v[4:5], v[16:17], v[0:1]
	v_pk_fma_f32 v[2:3], v[6:7], v[20:21], v[2:3]
	v_cvt_pk_bf16_f32 v170, v0, v1
	v_cvt_pk_bf16_f32 v171, v2, v3
	s_nop 1
	v_permlane16_swap_b32_e32 v168, v170
	v_permlane16_swap_b32_e32 v169, v171
	global_store_dwordx4 v[44:45], v[168:171], off offset:512
	v_pk_mul_f32 v[0:1], v[4:5], v[18:19]
	v_pk_mul_f32 v[2:3], v[6:7], v[22:23]
	v_pk_fma_f32 v[0:1], v[12:13], v[16:17], v[0:1] neg_lo:[0,0,1] neg_hi:[0,0,1]
	v_pk_fma_f32 v[2:3], v[14:15], v[20:21], v[2:3] neg_lo:[0,0,1] neg_hi:[0,0,1]
	v_cvt_pk_bf16_f32 v174, v24, v25
	v_cvt_pk_bf16_f32 v175, v26, v27
	v_cvt_pk_bf16_f32 v178, v0, v1
	v_cvt_pk_bf16_f32 v179, v2, v3
	s_nop 1
	v_permlane16_swap_b32_e32 v172, v174
	v_permlane16_swap_b32_e32 v173, v175
	global_store_dwordx4 v[44:45], v[172:175], off
	v_permlane16_swap_b32_e32 v176, v178
	v_permlane16_swap_b32_e32 v177, v179
	global_store_dwordx4 v[44:45], v[176:179], off offset:768
	s_add_i32 s46, s46, s90
	s_andn2_b64 vcc, exec, s[38:39]
	s_mov_b32 s0, s12
	s_mov_b64 s[42:43], s[18:19]
	s_mov_b64 s[40:41], s[34:35]
	v_readlane_b32 s20, v255, 27
	v_mov_b64_e32 v[236:237], 0x300
	s_cbranch_vccz .LBB0_65

.Lnm_pro:
	v_lshl_add_u64 v[112:113], s[88:89], 0, v[36:37]
	v_lshl_add_u64 v[114:115], s[88:89], 0, v[58:59]
	v_add_co_u32_e32 v112, vcc, 0x8a80000, v112
	s_nop 0
	v_addc_co_u32_e32 v113, vcc, 0, v113, vcc
	global_load_dwordx4 v[0:3], v[114:115], off
	global_load_dwordx4 v[4:7], v[114:115], off offset:1024
	global_load_dwordx4 v[8:11], v[112:113], off
	global_load_dwordx4 v[12:15], v[112:113], off offset:1024
	s_branch .LBB0_318
	s_nop 0
	s_nop 0
	s_nop 0
	s_nop 0
	s_nop 0
	s_nop 0
	s_nop 0
	s_nop 0
	s_nop 0
	s_nop 0
	s_nop 0
	s_nop 0
	s_nop 0
	s_nop 0
	s_nop 0
	s_nop 0
	s_nop 0
	s_nop 0
	s_nop 0
	s_nop 0
	s_nop 0
	s_nop 0
	s_nop 0
	s_nop 0
	s_nop 0
	s_nop 0
	s_nop 0
	s_nop 0
	s_nop 0
	s_nop 0
	s_nop 0
	s_nop 0
	s_nop 0
	s_nop 0
	s_nop 0
	s_nop 0
	s_nop 0
	s_nop 0
	s_nop 0
	s_nop 0
	s_nop 0
	s_nop 0
	s_nop 0
	s_nop 0
	s_nop 0
	s_nop 0
	s_nop 0
	s_nop 0
	s_nop 0
	s_nop 0
	s_nop 0
	s_nop 0
	s_nop 0
	s_nop 0
	s_nop 0
	s_nop 0
	s_nop 0
	s_nop 0
	s_nop 0
	s_nop 0
	s_nop 0
	s_nop 0
	s_nop 0
	s_nop 0
	s_nop 0
	s_nop 0
	s_nop 0
	s_nop 0
	s_nop 0
	s_nop 0
	s_nop 0
	s_nop 0
	s_nop 0
	s_nop 0
	s_nop 0
	s_nop 0
	s_nop 0
	s_nop 0
	s_nop 0
	s_nop 0
	s_nop 0
	s_nop 0
	s_nop 0
	s_nop 0
	s_nop 0
	s_nop 0
	s_nop 0
	s_nop 0
	s_nop 0
	s_nop 0
	s_nop 0
	s_nop 0
	s_nop 0
	s_nop 0
	s_nop 0
	s_nop 0
	s_nop 0
	s_nop 0
	s_nop 0
	s_nop 0
	s_nop 0
	s_nop 0
	s_nop 0
	s_nop 0
	s_nop 0
	s_nop 0
	s_nop 0
	s_nop 0
	s_nop 0
	s_nop 0
	s_nop 0
	s_nop 0
	s_nop 0
	s_nop 0
	s_nop 0
	s_nop 0
	s_nop 0
	s_nop 0
	s_nop 0
	s_nop 0
	s_nop 0
	s_nop 0
	s_nop 0
	s_nop 0
	s_nop 0
	s_nop 0
	s_nop 0
	s_nop 0
	s_nop 0
	s_nop 0
	s_nop 0
	s_nop 0
	s_nop 0
	s_nop 0
	s_nop 0
	s_nop 0
	s_nop 0
	s_nop 0
	s_nop 0
	s_nop 0
	s_nop 0
	s_nop 0
	s_nop 0
	s_nop 0
	s_nop 0
	s_nop 0
	s_nop 0
	s_nop 0
	s_nop 0
	s_nop 0
	s_nop 0
	s_nop 0
	s_nop 0
	s_nop 0
	s_nop 0
	s_nop 0
	s_nop 0
	s_nop 0
	s_nop 0
	s_nop 0
	s_nop 0
	s_nop 0
	s_nop 0
	s_nop 0
	s_nop 0
	s_nop 0
	s_nop 0
	s_nop 0
	s_nop 0
	s_nop 0
	s_nop 0
	s_nop 0
	s_nop 0
	s_nop 0
	s_nop 0
	s_nop 0
	s_nop 0
	s_nop 0
	s_nop 0
	s_nop 0
	s_nop 0
	s_nop 0
	s_nop 0
	s_nop 0
	s_nop 0
	s_nop 0
	s_nop 0
	s_nop 0
	s_nop 0
	s_nop 0
	s_nop 0
	s_nop 0
	s_nop 0
	s_nop 0
	s_nop 0
	s_nop 0
	s_nop 0
	s_nop 0
	s_nop 0
	s_nop 0
	s_nop 0
	s_nop 0
	s_nop 0
	s_nop 0
	s_nop 0
	s_nop 0
	s_nop 0
	s_nop 0
	s_nop 0
	s_nop 0
	s_nop 0
	s_nop 0
	s_nop 0
	s_nop 0
	s_nop 0
	s_nop 0
	s_nop 0
	s_nop 0
	s_nop 0
	s_nop 0
	s_nop 0
	s_nop 0
	s_nop 0
	s_nop 0
	s_nop 0
	s_nop 0
	s_nop 0
	s_nop 0
	s_nop 0
	s_nop 0
	s_nop 0
	s_nop 0
	s_nop 0
	s_nop 0
	s_nop 0
	s_nop 0
	s_nop 0
	s_nop 0
	s_nop 0
	s_nop 0
	s_nop 0
	s_nop 0
	s_nop 0
	s_nop 0
	s_nop 0
	s_nop 0
	s_nop 0
	s_nop 0
	s_nop 0
	s_nop 0
	s_nop 0
	s_nop 0
	s_nop 0
	s_nop 0
	s_nop 0
	s_nop 0
	s_nop 0
	s_nop 0
	s_nop 0
	s_nop 0
	s_nop 0
	s_nop 0
	s_nop 0
	s_nop 0
	s_nop 0
	s_nop 0
	s_nop 0
	s_nop 0
	s_nop 0
	s_nop 0
	s_nop 0
	s_nop 0
	s_nop 0
	s_nop 0
	s_nop 0
	s_nop 0
	s_nop 0
	s_nop 0
	s_nop 0
	s_nop 0
	s_nop 0
	s_nop 0
	s_nop 0
	s_nop 0
	s_nop 0
	s_nop 0
	s_nop 0
	s_nop 0
	s_nop 0
	s_nop 0
	s_nop 0
	s_nop 0
	s_nop 0
	s_nop 0
	s_nop 0
	s_nop 0
	s_nop 0
	s_nop 0
	s_nop 0
	s_nop 0
	s_nop 0
	s_nop 0
	s_nop 0
	s_nop 0
	s_nop 0
	s_nop 0
	s_nop 0
	s_nop 0
	s_nop 0
	s_nop 0
	s_nop 0
	s_nop 0
	s_nop 0
	s_nop 0
	s_nop 0
	s_nop 0
	s_nop 0
	s_nop 0
	s_nop 0
	s_nop 0
	s_nop 0
	s_nop 0
	s_nop 0
	s_nop 0
	s_nop 0
	s_nop 0
	s_nop 0
	s_nop 0
	s_nop 0
	s_nop 0
	s_nop 0
	s_nop 0
	s_nop 0
	s_nop 0
	s_nop 0
	s_nop 0
	s_nop 0
	s_nop 0
	s_nop 0
	s_nop 0
	s_nop 0
	s_nop 0
	s_nop 0
	s_nop 0
	s_nop 0
	s_nop 0
	s_nop 0
	s_nop 0
	s_nop 0
	s_nop 0
	s_nop 0
	s_nop 0
	s_nop 0
	s_nop 0
	s_nop 0
	s_nop 0
	s_nop 0
	s_nop 0
	s_nop 0
	s_nop 0
	s_nop 0
	s_nop 0
	s_nop 0
	s_nop 0
	s_nop 0
	s_nop 0
	s_nop 0
	s_nop 0
	s_nop 0
	s_nop 0
	s_nop 0
	s_nop 0
	s_nop 0
	s_nop 0
	s_nop 0
	s_nop 0
	s_nop 0
	s_nop 0
	s_nop 0
	s_nop 0
	s_nop 0
	s_nop 0
	s_nop 0
	s_nop 0
	s_nop 0
	s_nop 0
	s_nop 0
	s_nop 0
	s_nop 0
	s_nop 0
	s_nop 0
	s_nop 0
	s_nop 0
	s_nop 0
	s_nop 0
	s_nop 0
	s_nop 0
	s_nop 0
	s_nop 0
	s_nop 0
	s_nop 0
	s_nop 0
	s_nop 0
	s_nop 0
	s_nop 0
	s_nop 0
	s_nop 0
	s_nop 0
	s_nop 0
	s_nop 0
	s_nop 0
	s_nop 0
	s_nop 0
	s_nop 0
	s_nop 0
	s_nop 0
	s_nop 0
	s_nop 0
	s_nop 0
	s_nop 0
	s_nop 0
	s_nop 0
	s_nop 0
	s_nop 0
	s_nop 0
	s_nop 0
	s_nop 0
	s_nop 0
	s_nop 0
	s_nop 0
	s_nop 0
	s_nop 0
	s_nop 0
	s_nop 0
	s_nop 0
	s_nop 0
	s_nop 0
	s_nop 0
	s_nop 0
	s_nop 0
.Lfbp_addr:
	v_alignbit_b32 v212, v191, v190, 2
	v_add_u32_e32 v214, v201, v212
	v_ashrrev_i32_e32 v215, 31, v214
	v_lshlrev_b64 v[236:237], 11, v[214:215]
	v_lshl_add_u64 v[236:237], s[6:7], 0, v[236:237]
	v_lshl_add_u64 v[236:237], v[236:237], 0, v[128:129]
	v_add_u32_e32 v214, v202, v212
	v_ashrrev_i32_e32 v215, 31, v214
	v_lshlrev_b64 v[238:239], 11, v[214:215]
	v_lshl_add_u64 v[238:239], s[6:7], 0, v[238:239]
	v_lshl_add_u64 v[238:239], v[238:239], 0, v[128:129]
	v_mbcnt_lo_u32_b32 v220, -1, 0
	v_mbcnt_hi_u32_b32 v220, -1, v220
	v_and_b32_e32 v220, 32, v220
	v_lshrrev_b32_e32 v220, 2, v220
	v_mov_b32_e32 v221, 0
	v_lshl_add_u64 v[236:237], v[236:237], 0, v[220:221]
	v_lshl_add_u64 v[238:239], v[238:239], 0, v[220:221]
	s_branch .Lfbp_addrd

.Lfa1_x:
	v_mbcnt_lo_u32_b32 v196, -1, 0
	v_mbcnt_hi_u32_b32 v196, -1, v196
	v_and_b32_e32 v196, 16, v196
	v_lshrrev_b32_e32 v197, 1, v196
	v_add_u32_e32 v196, v196, v197
	v_mov_b32_e32 v197, 0
	s_setprio 0
	v_mov_b32_e32 v115, v108
	s_barrier
	s_lshl_b32 s0, s0, 9
	v_mul_lo_u32 v124, v115, v110
	v_cvt_f32_i32_e32 v125, v124
	v_add_u32_e32 v127, v124, v115
	v_cvt_f32_i32_e32 v130, v127
	v_lshl_add_u32 v128, v115, 18, s0
	v_mul_f32_e32 v125, 0x39c90fdb, v125
	v_mul_f32_e32 v125, 0.15915494, v125
	v_cos_f32_e32 v124, v125
	v_sin_f32_e32 v126, v125
	v_mul_f32_e32 v125, 0x39c90fdb, v130
	v_add_u32_e32 v130, v127, v115
	v_cvt_f32_i32_e32 v131, v130
	v_add_u32_e32 v130, v130, v115
	v_cvt_f32_i32_e32 v133, v130
	v_mul_f32_e32 v127, 0.15915494, v125
	v_mul_f32_e32 v131, 0x39c90fdb, v131
	v_mul_f32_e32 v131, 0.15915494, v131
	v_cos_f32_e32 v132, v131
	v_sin_f32_e32 v134, v131
	v_mul_f32_e32 v131, 0x39c90fdb, v133
	v_mul_f32_e32 v131, 0.15915494, v131
	v_cos_f32_e32 v125, v127
	v_sin_f32_e32 v127, v127
	v_sin_f32_e32 v135, v131
	v_cos_f32_e32 v133, v131
	v_readlane_b32 s48, v252, 0
	v_pk_mul_f32 v[136:137], v[156:157], v[126:127]
	v_pk_mul_f32 v[138:139], v[158:159], v[134:135]
	s_branch .Lfa1_xd
